# v046_attnwait
# speedup vs baseline: 1.0053x; 1.0053x over previous
; __device__ __forceinline__ void attn_wave_item(const Params& p, int witem, const int tidx) {
;   const int lane = tidx & 63, n = lane & 31, half = lane >> 5, wid = tidx >> 6;
;   const int qt = witem & 127, h = (witem >> 7) & 15, b = witem >> 11;
;   const int t0 = qt * 32;
;   const u16* proj = (const u16*)(p.ws + WS_PROJ);
;   u16* yraw = (u16*)(p.ws + WS_YRAW);
;   char* qlds = smem + wid * 8192 + lane * 16;
;   {
;     const u16* qp = proj + (size_t)(b * SEQ + t0 + n) * DIN + OFF_Q + h * 128 + 8 * half;
;     u32x4 qv[8];
; #pragma unroll
;     for (int ks = 0; ks < 8; ++ks) qv[ks] = *reinterpret_cast<const u32x4*>(qp + ks * 16);
; #pragma unroll
;     for (int ks = 0; ks < 8; ++ks) *reinterpret_cast<u32x4*>(qlds + ks * 1024) = qv[ks];
;   }
;   f32x16 O[4];
; #pragma unroll
;   for (int d = 0; d < 4; ++d)
; #pragma unroll
;     for (int i = 0; i < 16; ++i) O[d][i] = 0.f;
;   float R = 1.f;
;   const char* kbase = (const char*)(p.ws + WS_KP) + ((size_t)(b * 16 + h) * 128) * 8192 + lane * 16;
;   const char* vbase = (const char*)(p.ws + WS_VT) + ((size_t)(b * 16 + h) * 128) * 8192 + lane * 16;
;   u32x4 kf[8];
;   {
;     const char* kp = kbase + (size_t)qt * 8192;
; #pragma unroll
;     for (int ks = 0; ks < 8; ++ks) kf[ks] = *reinterpret_cast<const u32x4*>(kp + ks * 1024);
;   }
.LBB0_115:
	s_andn2_b64 vcc, exec, s[6:7]
	s_cbranch_vccnz .LBB0_123
	s_lshl_b32 s42, s64, 3
	v_add_u32_e32 v0, s42, v97
	v_add_u32_e32 v0, 0xfffff400, v0
	v_and_b32_e32 v169, 0x7f, v0
	v_ashrrev_i32_e32 v35, 11, v0
	v_and_b32_e32 v38, 31, v164
	v_bfe_u32 v34, v0, 7, 4
	v_lshlrev_b32_e32 v0, 5, v169
	v_lshlrev_b32_e32 v1, 12, v35
	v_or3_b32 v166, v1, v0, v38
	v_mov_b64_e32 v[0:1], s[86:87]
	v_bfe_u32 v32, v164, 5, 1
	v_mad_i64_i32 v[0:1], s[6:7], v166, s63, v[0:1]
	v_lshlrev_b32_e32 v2, 8, v34
	v_mov_b32_e32 v3, v163
	v_lshl_add_u64 v[0:1], v[0:1], 0, v[2:3]
	v_lshlrev_b32_e32 v2, 4, v32
	v_lshl_add_u64 v[0:1], v[0:1], 0, v[2:3]
	s_mov_b64 s[6:7], 0x14901000
	v_lshl_add_u64 v[28:29], v[0:1], 0, s[6:7]
	s_mov_b32 s6, 0x14901000
	v_add_co_u32_e32 v0, vcc, s6, v0
	v_lshlrev_b32_e32 v37, 7, v164
	s_nop 0
	v_addc_co_u32_e32 v1, vcc, 0, v1, vcc
	global_load_dwordx4 v[0:3], v[0:1], off
	s_nop 0
	global_load_dwordx4 v[4:7], v[28:29], off offset:32
	global_load_dwordx4 v[8:11], v[28:29], off offset:64
	global_load_dwordx4 v[12:15], v[28:29], off offset:96
	global_load_dwordx4 v[16:19], v[28:29], off offset:128
	global_load_dwordx4 v[20:23], v[28:29], off offset:160
	global_load_dwordx4 v[24:27], v[28:29], off offset:192
	s_nop 0
	global_load_dwordx4 v[28:31], v[28:29], off offset:224
	v_and_b32_e32 v41, 64, v215
	v_lshlrev_b32_e32 v168, 7, v34
	v_lshl_or_b32 v34, v35, 4, v34
	v_and_b32_e32 v36, 63, v164
	v_xor_b32_e32 v40, 32, v215
	v_and_b32_e32 v37, 0xffffe000, v37
	v_lshlrev_b32_e32 v165, 2, v32
	v_add_u32_e32 v32, 64, v41
	v_ashrrev_i32_e32 v35, 31, v34
	v_lshlrev_b32_e32 v162, 4, v36
	v_cmp_gt_u32_e32 vcc, 32, v36
	v_add_u32_e32 v36, 32, v37
	v_cmp_lt_i32_e64 s[6:7], v40, v32
	v_or_b32_e32 v37, 1, v165
	v_lshlrev_b64 v[34:35], 20, v[34:35]
	v_cndmask_b32_e64 v32, v215, v40, s[6:7]
	v_add_u32_e32 v173, v36, v162
	v_cmp_lt_u32_e64 s[8:9], v37, v38
	v_lshl_add_u64 v[36:37], s[70:71], 0, v[34:35]
	v_mov_b32_e32 v33, v163
	v_lshlrev_b32_e32 v178, 2, v32
	v_lshlrev_b32_e32 v32, 13, v169
	v_lshl_add_u64 v[170:171], v[36:37], 0, v[162:163]
	v_lshl_add_u64 v[32:33], v[170:171], 0, v[32:33]
	global_load_dwordx4 v[98:101], v[32:33], off
	global_load_dwordx4 v[102:105], v[32:33], off offset:1024
	global_load_dwordx4 v[106:109], v[32:33], off offset:2048
	global_load_dwordx4 v[110:113], v[32:33], off offset:3072
	v_add_co_u32_e64 v32, s[20:21], s56, v32
	v_lshrrev_b32_e32 v39, 6, v164
	s_nop 0
	v_addc_co_u32_e64 v33, s[20:21], 0, v33, s[20:21]
	global_load_dwordx4 v[114:117], v[32:33], off
	global_load_dwordx4 v[118:121], v[32:33], off offset:1024
	global_load_dwordx4 v[122:125], v[32:33], off offset:2048
	global_load_dwordx4 v[126:129], v[32:33], off offset:3072
	v_or_b32_e32 v40, 2, v165
	v_or_b32_e32 v41, 3, v165
	v_or_b32_e32 v42, 8, v165
	v_or_b32_e32 v43, 9, v165
	v_or_b32_e32 v44, 10, v165
	v_mov_b32_e32 v48, 0
	v_cmp_lt_u32_e64 s[6:7], v165, v38
	v_cmp_lt_u32_e64 s[10:11], v40, v38
	v_cmp_lt_u32_e64 s[12:13], v41, v38
	v_cmp_lt_u32_e64 s[14:15], v42, v38
	v_cmp_lt_u32_e64 s[16:17], v43, v38
	v_cmp_lt_u32_e64 s[18:19], v44, v38
	v_ashrrev_i32_e32 v167, 31, v166
	s_movk_i32 s58, 0x1000
	v_mov_b32_e32 v177, 1.0
	s_mov_b64 s[88:89], 0
	s_mov_b64 s[48:49], 0
	v_mov_b32_e32 v49, v48
	v_mov_b32_e32 v50, v48
	v_mov_b32_e32 v51, v48
	v_mov_b32_e32 v52, v48
	v_mov_b32_e32 v53, v48
	v_mov_b32_e32 v54, v48
	v_mov_b32_e32 v55, v48
	v_mov_b32_e32 v56, v48
	v_mov_b32_e32 v57, v48
	v_mov_b32_e32 v58, v48
	v_mov_b32_e32 v59, v48
	v_mov_b32_e32 v60, v48
	v_mov_b32_e32 v61, v48
	v_mov_b32_e32 v62, v48
	v_mov_b32_e32 v63, v48
	v_mov_b32_e32 v32, v48
	s_waitcnt vmcnt(15)
	ds_write_b128 v173, v[0:3]
	s_waitcnt vmcnt(14)
	ds_write_b128 v173, v[4:7] offset:1024
	s_waitcnt vmcnt(13)
	ds_write_b128 v173, v[8:11] offset:2048
	s_waitcnt vmcnt(12)
	ds_write_b128 v173, v[12:15] offset:3072
	s_waitcnt vmcnt(11)
	ds_write_b128 v173, v[16:19] offset:4096
	s_waitcnt vmcnt(10)
	ds_write_b128 v173, v[20:23] offset:5120
	s_waitcnt vmcnt(9)
	ds_write_b128 v173, v[24:27] offset:6144
	s_waitcnt vmcnt(8)
	ds_write_b128 v173, v[28:31] offset:7168
	v_or_b32_e32 v0, 11, v165
	v_cmp_lt_u32_e64 s[20:21], v0, v38
	v_or_b32_e32 v0, 16, v165
	v_cmp_lt_u32_e64 s[22:23], v0, v38
	v_or_b32_e32 v0, 17, v165
	v_cmp_lt_u32_e64 s[24:25], v0, v38
	v_or_b32_e32 v0, 18, v165
	v_cmp_lt_u32_e64 s[26:27], v0, v38
	v_or_b32_e32 v0, 19, v165
	v_cmp_lt_u32_e64 s[28:29], v0, v38
	v_or_b32_e32 v0, 24, v165
	v_cmp_lt_u32_e64 s[30:31], v0, v38
	v_or_b32_e32 v0, 25, v165
	v_cmp_lt_u32_e64 s[34:35], v0, v38
	v_or_b32_e32 v0, 26, v165
	v_cmp_lt_u32_e64 s[36:37], v0, v38
	v_or_b32_e32 v0, 27, v165
	v_cmp_lt_u32_e64 s[38:39], v0, v38
	v_add_u16_e32 v0, s42, v39
	v_and_b32_e32 v0, 0x7f, v0
	v_lshlrev_b32_e32 v172, 13, v0
	v_or3_b32 v34, v34, v172, v162
	v_lshl_add_u64 v[174:175], s[86:87], 0, v[34:35]
	v_mov_b32_e32 v33, v48
	v_mov_b32_e32 v34, v48
	v_mov_b32_e32 v35, v48
	v_mov_b32_e32 v36, v48
	v_mov_b32_e32 v37, v48
	v_mov_b32_e32 v38, v48
	v_mov_b32_e32 v39, v48
	v_mov_b32_e32 v40, v48
	v_mov_b32_e32 v41, v48
	v_mov_b32_e32 v42, v48
	v_mov_b32_e32 v43, v48
	v_mov_b32_e32 v44, v48
	v_mov_b32_e32 v45, v48
	v_mov_b32_e32 v46, v48
	v_mov_b32_e32 v47, v48
	v_mov_b32_e32 v16, v48
	v_mov_b32_e32 v17, v48
	v_mov_b32_e32 v18, v48
	v_mov_b32_e32 v19, v48
	v_mov_b32_e32 v20, v48
	v_mov_b32_e32 v21, v48
	v_mov_b32_e32 v22, v48
	v_mov_b32_e32 v23, v48
	v_mov_b32_e32 v24, v48
	v_mov_b32_e32 v25, v48
	v_mov_b32_e32 v26, v48
	v_mov_b32_e32 v27, v48
	v_mov_b32_e32 v28, v48
	v_mov_b32_e32 v29, v48
	v_mov_b32_e32 v30, v48
	v_mov_b32_e32 v31, v48
	v_mov_b32_e32 v0, v48
	v_mov_b32_e32 v1, v48
	v_mov_b32_e32 v2, v48
	v_mov_b32_e32 v3, v48
	v_mov_b32_e32 v4, v48
	v_mov_b32_e32 v5, v48
	v_mov_b32_e32 v6, v48
	v_mov_b32_e32 v7, v48
	v_mov_b32_e32 v8, v48
	v_mov_b32_e32 v9, v48
	v_mov_b32_e32 v10, v48
	v_mov_b32_e32 v11, v48
	v_mov_b32_e32 v12, v48
	v_mov_b32_e32 v13, v48
	v_mov_b32_e32 v14, v48
	v_mov_b32_e32 v15, v48
	s_branch .LBB0_119

; __device__ __forceinline__ void attn_wave_item(const Params& p, int witem, const int tidx) {
;     ...
;     u32x4 vf[8], kn[8];
;     {
;       const int tn = tile > 0 ? tile - 1 : 0;
;       const char* vp = vbase + (size_t)tile * 8192;
;       const char* kp = kbase + (size_t)tn * 8192;
; #pragma unroll
;       for (int i = 0; i < 8; ++i) vf[i] = *reinterpret_cast<const u32x4*>(vp + i * 1024);
; #pragma unroll
;       for (int ks = 0; ks < 8; ++ks) kn[ks] = *reinterpret_cast<const u32x4*>(kp + ks * 1024);
;     }
;     __builtin_amdgcn_sched_barrier(0);
;     f32x16 S, S2;
; #pragma unroll
;     for (int i = 0; i < 16; ++i) { S[i] = 0.f; S2[i] = 0.f; }
; #pragma unroll
;     for (int ks = 0; ks < 8; ks += 2) {
;       u32x4 qa = *reinterpret_cast<const u32x4*>(qlds + ks * 1024);
;       u32x4 qb = *reinterpret_cast<const u32x4*>(qlds + (ks + 1) * 1024);
;       S = __builtin_amdgcn_mfma_f32_32x32x16_bf16(as_bf16x8(kf[ks]), as_bf16x8(qa), S, 0, 0, 0);
;       S2 = __builtin_amdgcn_mfma_f32_32x32x16_bf16(as_bf16x8(kf[ks + 1]), as_bf16x8(qb), S2, 0, 0, 0);
;     }
; #pragma unroll
;     for (int i = 0; i < 16; ++i) S[i] += S2[i];
;     const bool diag = (tile == qt);
;     float be[16], om[16];
; #pragma unroll
;     for (int r = 0; r < 16; ++r) {
;       float z = S[r];
;       float e = __builtin_amdgcn_exp2f(-fabsf(z));
;       float rr = __builtin_amdgcn_rcpf(1.f + e);
;       float sm = e * rr;
;       int kl = (r & 3) + 8 * (r >> 2) + 4 * half;
;       bool v = !diag || (kl < n);
;       bool pos = z >= 0.f;
;       be[r] = v ? (pos ? rr : sm) : 0.f;
;       om[r] = v ? (pos ? sm : rr) : 1.f;
;     }
.LBB0_119:
	ds_read_b128 v[226:229], v173
	ds_read_b128 v[84:87], v173 offset:1024
	ds_read_b128 v[204:207], v173 offset:2048
	ds_read_b128 v[222:225], v173 offset:3072
	v_lshl_add_u64 v[68:69], v[174:175], 0, s[48:49]
	s_mov_b32 s42, 0x20900000
	v_add_co_u32_e64 v72, s[42:43], s42, v68
	v_sub_u32_e64 v162, v169, 1 clamp
	s_nop 0
	v_addc_co_u32_e64 v73, s[42:43], 0, v69, s[42:43]
	s_mov_b32 s42, 0x20901000
	s_nop 0
	v_add_co_u32_e64 v68, s[42:43], s42, v68
	v_lshlrev_b64 v[70:71], 13, v[162:163]
	s_nop 0
	v_addc_co_u32_e64 v69, s[42:43], 0, v69, s[42:43]
	global_load_dwordx4 v[154:157], v[72:73], off offset:1024
	global_load_dwordx4 v[150:153], v[72:73], off offset:2048
	global_load_dwordx4 v[142:145], v[72:73], off offset:3072
	global_load_dwordx4 v[158:161], v[68:69], off offset:-4096
	global_load_dwordx4 v[146:149], v[68:69], off
	global_load_dwordx4 v[138:141], v[68:69], off offset:1024
	global_load_dwordx4 v[134:137], v[68:69], off offset:2048
	global_load_dwordx4 v[130:133], v[68:69], off offset:3072
	s_waitcnt vmcnt(12)
	v_mov_b64_e32 v[198:199], v[112:113]
	v_mov_b64_e32 v[202:203], v[108:109]
	v_mov_b64_e32 v[80:81], v[102:103]
	v_mov_b64_e32 v[64:65], v[98:99]
	v_lshl_add_u64 v[68:69], v[170:171], 0, v[70:71]
	v_mov_b64_e32 v[196:197], v[110:111]
	v_mov_b64_e32 v[200:201], v[106:107]
	v_mov_b64_e32 v[82:83], v[104:105]
	v_mov_b64_e32 v[66:67], v[100:101]
	global_load_dwordx4 v[98:101], v[68:69], off
	global_load_dwordx4 v[102:105], v[68:69], off offset:1024
	global_load_dwordx4 v[106:109], v[68:69], off offset:2048
	global_load_dwordx4 v[110:113], v[68:69], off offset:3072
	v_add_co_u32_e64 v68, s[42:43], s58, v68
	s_waitcnt vmcnt(12)
	v_mov_b64_e32 v[182:183], v[128:129]
	v_mov_b64_e32 v[186:187], v[124:125]
	v_mov_b64_e32 v[190:191], v[120:121]
	v_mov_b64_e32 v[194:195], v[116:117]
	v_addc_co_u32_e64 v69, s[42:43], 0, v69, s[42:43]
	v_mov_b64_e32 v[180:181], v[126:127]
	v_mov_b64_e32 v[184:185], v[122:123]
	v_mov_b64_e32 v[188:189], v[118:119]
	v_mov_b64_e32 v[192:193], v[114:115]
	global_load_dwordx4 v[114:117], v[68:69], off
	global_load_dwordx4 v[118:121], v[68:69], off offset:1024
	global_load_dwordx4 v[122:125], v[68:69], off offset:2048
	global_load_dwordx4 v[126:129], v[68:69], off offset:3072
	s_cmp_lg_u32 s48, 0
	s_cselect_b64 s[50:51], -1, 0
	s_waitcnt lgkmcnt(3)
	s_setprio 1
	v_mfma_f32_32x32x16_bf16 v[64:79], v[64:67], v[226:229], 0
	s_or_b64 s[44:45], s[6:7], s[50:51]
	s_waitcnt lgkmcnt(2)
	v_mfma_f32_32x32x16_bf16 v[80:95], v[80:83], v[84:87], 0
	s_waitcnt lgkmcnt(1)
	v_mfma_f32_32x32x16_bf16 v[64:79], v[200:203], v[204:207], v[64:79]
	s_waitcnt lgkmcnt(0)
	v_mfma_f32_32x32x16_bf16 v[80:95], v[196:199], v[222:225], v[80:95]
	ds_read_b128 v[196:199], v173 offset:4096
	ds_read_b128 v[200:203], v173 offset:5120
	s_waitcnt lgkmcnt(1)
	v_mfma_f32_32x32x16_bf16 v[64:79], v[192:195], v[196:199], v[64:79]
	s_waitcnt lgkmcnt(0)
	v_mfma_f32_32x32x16_bf16 v[80:95], v[188:191], v[200:203], v[80:95]
	ds_read_b128 v[188:191], v173 offset:6144
	ds_read_b128 v[192:195], v173 offset:7168
	s_waitcnt lgkmcnt(1)
	v_mfma_f32_32x32x16_bf16 v[64:79], v[184:187], v[188:191], v[64:79]
	s_waitcnt lgkmcnt(0)
	v_mfma_f32_32x32x16_bf16 v[80:95], v[180:183], v[192:195], v[80:95]
	s_setprio 0
	s_nop 11
	v_add_f32_e32 v64, v64, v80
	v_exp_f32_e64 v80, -|v64|
	v_add_f32_e32 v65, v65, v81
	v_add_f32_e32 v66, v66, v82
	v_exp_f32_e64 v82, -|v65|
	v_add_f32_e32 v81, 1.0, v80
	v_rcp_f32_e32 v81, v81
	v_add_f32_e32 v67, v67, v83
	v_add_f32_e32 v83, 1.0, v82
	v_cmp_le_f32_e64 s[42:43], 0, v64
	v_mul_f32_e32 v80, v80, v81
	v_rcp_f32_e32 v83, v83
	v_cndmask_b32_e64 v64, v80, v81, s[42:43]
	v_add_f32_e32 v68, v68, v84
	v_cndmask_b32_e64 v84, 0, v64, s[44:45]
	v_cndmask_b32_e64 v64, v81, v80, s[42:43]
	v_exp_f32_e64 v81, -|v66|
	v_cndmask_b32_e64 v80, 1.0, v64, s[44:45]
	v_mul_f32_e32 v64, v82, v83
	v_cmp_le_f32_e64 s[42:43], 0, v65
	s_or_b64 s[44:45], s[8:9], s[50:51]
	v_add_f32_e32 v69, v69, v85
	v_cndmask_b32_e64 v65, v64, v83, s[42:43]
	v_cndmask_b32_e64 v64, v83, v64, s[42:43]
	v_cndmask_b32_e64 v82, 0, v65, s[44:45]
	v_add_f32_e32 v65, 1.0, v81
	v_cndmask_b32_e64 v83, 1.0, v64, s[44:45]
	v_exp_f32_e64 v64, -|v67|
	v_rcp_f32_e32 v65, v65
	v_cmp_le_f32_e64 s[42:43], 0, v66
	s_or_b64 s[44:45], s[10:11], s[50:51]
	v_add_f32_e32 v85, 1.0, v64
	v_mul_f32_e32 v81, v81, v65
	v_rcp_f32_e32 v85, v85
	v_cndmask_b32_e64 v66, v81, v65, s[42:43]
	v_cndmask_b32_e64 v65, v65, v81, s[42:43]
	v_cndmask_b32_e64 v81, 1.0, v65, s[44:45]
	v_exp_f32_e64 v65, -|v68|
	v_mul_f32_e32 v64, v64, v85
	v_cmp_le_f32_e64 s[42:43], 0, v67
	v_exp_f32_e64 v67, -|v69|
	v_add_f32_e32 v70, v70, v86
	v_cndmask_b32_e64 v86, 0, v66, s[44:45]
	v_cndmask_b32_e64 v66, v64, v85, s[42:43]
	s_or_b64 s[44:45], s[12:13], s[50:51]
	v_add_f32_e32 v71, v71, v87
	v_cndmask_b32_e64 v87, 0, v66, s[44:45]
	v_add_f32_e32 v66, 1.0, v65
	v_rcp_f32_e32 v66, v66
	v_cndmask_b32_e64 v64, v85, v64, s[42:43]
	v_cmp_le_f32_e64 s[42:43], 0, v68
	v_add_f32_e32 v68, 1.0, v67
	v_rcp_f32_e32 v68, v68
	v_cndmask_b32_e64 v85, 1.0, v64, s[44:45]
	v_mul_f32_e32 v64, v65, v66
	v_cndmask_b32_e64 v65, v64, v66, s[42:43]
	s_or_b64 s[44:45], s[14:15], s[50:51]
	v_add_f32_e32 v72, v72, v88
	v_cndmask_b32_e64 v88, 0, v65, s[44:45]
	v_mul_f32_e32 v65, v67, v68
	v_exp_f32_e64 v67, -|v70|
	v_cndmask_b32_e64 v64, v66, v64, s[42:43]
	v_cmp_le_f32_e64 s[42:43], 0, v69
	v_cndmask_b32_e64 v64, 1.0, v64, s[44:45]
	s_or_b64 s[44:45], s[16:17], s[50:51]
	v_cndmask_b32_e64 v66, v65, v68, s[42:43]
	v_add_f32_e32 v73, v73, v89
	v_cndmask_b32_e64 v89, 0, v66, s[44:45]
	v_add_f32_e32 v66, 1.0, v67
	v_cndmask_b32_e64 v65, v68, v65, s[42:43]
; __device__ __forceinline__ void attn_wave_item(const Params& p, int witem, const int tidx) {
;     ...
;     float be[16], om[16];
; #pragma unroll
;     for (int r = 0; r < 16; ++r) {
;       float z = S[r];
;       float e = __builtin_amdgcn_exp2f(-fabsf(z));
;       float rr = __builtin_amdgcn_rcpf(1.f + e);
;       float sm = e * rr;
;       int kl = (r & 3) + 8 * (r >> 2) + 4 * half;
;       bool v = !diag || (kl < n);
;       bool pos = z >= 0.f;
;       be[r] = v ? (pos ? rr : sm) : 0.f;
;       om[r] = v ? (pos ? sm : rr) : 1.f;
;     }
;     float gp[4], pgp[4];
; #pragma unroll
;     for (int gi = 0; gi < 4; ++gi) {
;       gp[gi] = (om[4 * gi] * om[4 * gi + 1]) * (om[4 * gi + 2] * om[4 * gi + 3]);
;       pgp[gi] = __shfl_xor(gp[gi], 32, 64);
;     }
;     float w[16];
;     float run = R;
; #pragma unroll
;     ...
;       float a = (half == 0) ? (run * pgp[gi]) : run;
; #pragma unroll
;       for (int r = 3; r >= 0; --r) {
;         int ri = 4 * gi + r;
;         w[ri] = be[ri] * a;
;         a *= om[ri];
;       }
;       run *= gp[gi] * pgp[gi];
;     }
;     R = run;
;     __builtin_amdgcn_sched_barrier(0);
;     bf16x8 pf[2];
; #pragma unroll
;     for (int m = 0; m < 2; ++m) {
;       u32x4 t;
;       t.x = pack2(w[8 * m + 0], w[8 * m + 1]);
;       t.y = pack2(w[8 * m + 2], w[8 * m + 3]);
;       t.z = pack2(w[8 * m + 4], w[8 * m + 5]);
;       t.w = pack2(w[8 * m + 6], w[8 * m + 7]);
;       pf[m] = as_bf16x8(t);
;     }
; #pragma unroll
;     for (int dt = 0; dt < 4; ++dt)
; #pragma unroll
;       for (int m = 0; m < 2; ++m) O[dt] = __builtin_amdgcn_mfma_f32_32x32x16_bf16(as_bf16x8(vf[dt * 2 + m]), pf[m], O[dt], 0, 0, 0);
;     if (__all(R < 1.17549435e-38f)) break;
;     __builtin_amdgcn_sched_barrier(0);
; #pragma unroll
;     for (int i = 0; i < 8; ++i) kf[i] = kn[i];
;   }
	v_rcp_f32_e32 v69, v66
	v_cndmask_b32_e64 v66, 1.0, v65, s[44:45]
	v_exp_f32_e64 v65, -|v71|
	v_cmp_le_f32_e64 s[42:43], 0, v70
	v_mul_f32_e32 v67, v67, v69
	s_or_b64 s[44:45], s[18:19], s[50:51]
	v_add_f32_e32 v70, 1.0, v65
	v_rcp_f32_e32 v70, v70
	v_cndmask_b32_e64 v68, v67, v69, s[42:43]
	v_cndmask_b32_e64 v67, v69, v67, s[42:43]
	v_cndmask_b32_e64 v176, 1.0, v67, s[44:45]
	v_exp_f32_e64 v67, -|v72|
	v_mul_f32_e32 v65, v65, v70
	v_cmp_le_f32_e64 s[42:43], 0, v71
	v_add_f32_e32 v74, v74, v90
	v_cndmask_b32_e64 v90, 0, v68, s[44:45]
	v_cndmask_b32_e64 v68, v65, v70, s[42:43]
	s_or_b64 s[44:45], s[20:21], s[50:51]
	v_cndmask_b32_e64 v71, 0, v68, s[44:45]
	v_add_f32_e32 v68, 1.0, v67
	v_cndmask_b32_e64 v65, v70, v65, s[42:43]
	v_rcp_f32_e32 v69, v68
	v_cndmask_b32_e64 v68, 1.0, v65, s[44:45]
	v_exp_f32_e64 v65, -|v73|
	v_cmp_le_f32_e64 s[42:43], 0, v72
	v_mul_f32_e32 v67, v67, v69
	s_or_b64 s[44:45], s[22:23], s[50:51]
	v_add_f32_e32 v72, 1.0, v65
	v_rcp_f32_e32 v72, v72
	v_cndmask_b32_e64 v70, v67, v69, s[42:43]
	v_cndmask_b32_e64 v67, v69, v67, s[42:43]
	v_cmp_le_f32_e64 s[42:43], 0, v73
	v_mul_f32_e32 v65, v65, v72
	v_add_f32_e32 v75, v75, v91
	v_cndmask_b32_e64 v91, 0, v70, s[44:45]
	v_cndmask_b32_e64 v67, 1.0, v67, s[44:45]
	v_exp_f32_e64 v69, -|v74|
	v_cndmask_b32_e64 v70, v65, v72, s[42:43]
	s_or_b64 s[44:45], s[24:25], s[50:51]
	v_cndmask_b32_e64 v65, v72, v65, s[42:43]
	v_add_f32_e32 v77, v77, v93
	v_cndmask_b32_e64 v93, 1.0, v65, s[44:45]
	v_exp_f32_e64 v65, -|v75|
	v_add_f32_e32 v76, v76, v92
	v_cndmask_b32_e64 v92, 0, v70, s[44:45]
	v_add_f32_e32 v70, 1.0, v69
	v_rcp_f32_e32 v70, v70
	v_add_f32_e32 v73, 1.0, v65
	v_rcp_f32_e32 v73, v73
	v_cmp_le_f32_e64 s[42:43], 0, v74
	v_mul_f32_e32 v69, v69, v70
	s_or_b64 s[44:45], s[26:27], s[50:51]
	v_cndmask_b32_e64 v72, v69, v70, s[42:43]
	v_cndmask_b32_e64 v69, v70, v69, s[42:43]
	v_mul_f32_e32 v65, v65, v73
	v_cmp_le_f32_e64 s[42:43], 0, v75
	v_add_f32_e32 v78, v78, v94
	v_add_f32_e32 v79, v79, v95
	v_cndmask_b32_e64 v94, 0, v72, s[44:45]
	v_cndmask_b32_e64 v95, 1.0, v69, s[44:45]
	v_exp_f32_e64 v69, -|v76|
	v_cndmask_b32_e64 v70, v65, v73, s[42:43]
	s_or_b64 s[44:45], s[28:29], s[50:51]
	v_cndmask_b32_e64 v65, v73, v65, s[42:43]
	v_cndmask_b32_e64 v179, 1.0, v65, s[44:45]
	v_exp_f32_e64 v65, -|v77|
	v_cndmask_b32_e64 v162, 0, v70, s[44:45]
	v_add_f32_e32 v70, 1.0, v69
	v_rcp_f32_e32 v70, v70
	v_add_f32_e32 v73, 1.0, v65
	v_rcp_f32_e32 v73, v73
	v_cmp_le_f32_e64 s[42:43], 0, v76
	v_mul_f32_e32 v69, v69, v70
	s_or_b64 s[44:45], s[30:31], s[50:51]
	v_cndmask_b32_e64 v72, v69, v70, s[42:43]
	v_cndmask_b32_e64 v69, v70, v69, s[42:43]
	v_mul_f32_e32 v65, v65, v73
	v_cmp_le_f32_e64 s[42:43], 0, v77
	v_cndmask_b32_e64 v74, 0, v72, s[44:45]
	v_cndmask_b32_e64 v69, 1.0, v69, s[44:45]
	v_exp_f32_e64 v70, -|v78|
	v_cndmask_b32_e64 v72, v65, v73, s[42:43]
	s_or_b64 s[44:45], s[34:35], s[50:51]
	v_cndmask_b32_e64 v65, v73, v65, s[42:43]
	v_cndmask_b32_e64 v73, 1.0, v65, s[44:45]
	v_exp_f32_e64 v65, -|v79|
	v_cndmask_b32_e64 v75, 0, v72, s[44:45]
	v_add_f32_e32 v72, 1.0, v70
	v_rcp_f32_e32 v72, v72
	v_add_f32_e32 v77, 1.0, v65
	v_rcp_f32_e32 v77, v77
	v_cmp_le_f32_e64 s[42:43], 0, v78
	v_mul_f32_e32 v70, v70, v72
	s_or_b64 s[44:45], s[36:37], s[50:51]
	v_cndmask_b32_e64 v76, v70, v72, s[42:43]
	v_cndmask_b32_e64 v70, v72, v70, s[42:43]
	v_mul_f32_e32 v65, v65, v77
	v_cmp_le_f32_e64 s[42:43], 0, v79
	v_cndmask_b32_e64 v76, 0, v76, s[44:45]
	v_cndmask_b32_e64 v78, 1.0, v70, s[44:45]
	v_cndmask_b32_e64 v70, v65, v77, s[42:43]
	s_or_b64 s[44:45], s[38:39], s[50:51]
	v_cndmask_b32_e64 v65, v77, v65, s[42:43]
	v_cndmask_b32_e64 v77, 1.0, v65, s[44:45]
	v_mul_f32_e32 v65, v69, v73
	v_mul_f32_e32 v69, v78, v77
	v_mul_f32_e32 v69, v65, v69
	v_cndmask_b32_e64 v79, 0, v70, s[44:45]
	v_mul_f32_e32 v70, v80, v83
	ds_bpermute_b32 v80, v178, v69
	v_mul_f32_e32 v65, v67, v93
	v_mul_f32_e32 v67, v95, v179
	v_mul_f32_e32 v65, v65, v67
	ds_bpermute_b32 v67, v178, v65
	s_waitcnt lgkmcnt(1)
	v_mul_f32_e32 v180, v177, v80
	v_cndmask_b32_e32 v180, v177, v180, vcc
	v_mul_f32_e32 v77, v180, v77
	v_mul_f32_e32 v76, v76, v77
	v_mul_f32_e32 v77, v78, v77
	v_mul_f32_e32 v73, v73, v77
	v_mul_f32_e32 v69, v69, v80
	v_mul_f32_e32 v78, v75, v77
	v_mul_f32_e32 v77, v74, v73
	v_pk_mul_f32 v[74:75], v[176:177], v[68:69]
	s_waitcnt lgkmcnt(0)
	v_pk_mul_f32 v[64:65], v[64:65], v[66:67]
	v_mul_f32_e32 v67, v75, v67
	v_pk_mul_f32 v[64:65], v[64:65], v[74:75]
	ds_bpermute_b32 v73, v178, v64
	v_cndmask_b32_e32 v67, v75, v67, vcc
	v_mul_f32_e32 v74, v162, v67
	v_mul_f32_e32 v67, v179, v67
	v_mul_f32_e32 v75, v94, v67
	v_mul_f32_e32 v67, v95, v67
	v_mul_f32_e32 v80, v92, v67
	v_mul_f32_e32 v67, v93, v67
	v_mul_f32_e32 v91, v91, v67
	s_waitcnt lgkmcnt(0)
	v_mul_f32_e32 v67, v65, v73
	v_cndmask_b32_e32 v67, v65, v67, vcc
	v_mul_f32_e32 v72, v81, v85
	v_mul_f32_e32 v92, v71, v67
	v_mov_b32_e32 v71, v64
	v_mul_f32_e32 v67, v68, v67
	v_pk_mul_f32 v[68:69], v[70:71], v[72:73]
	ds_bpermute_b32 v64, v178, v68
	v_mul_f32_e32 v90, v90, v67
	v_mul_f32_e32 v67, v176, v67
	v_mul_f32_e32 v70, v89, v67
	v_mul_f32_e32 v66, v66, v67
	s_waitcnt lgkmcnt(0)
	v_pk_mul_f32 v[72:73], v[68:69], v[64:65]
	v_mul_f32_e32 v79, v180, v79
	v_mul_f32_e32 v64, v73, v64
	v_cndmask_b32_e32 v64, v73, v64, vcc
	v_mul_f32_e32 v65, v87, v64
	v_mul_f32_e32 v64, v85, v64
	v_mul_f32_e32 v67, v86, v64
	v_mul_f32_e32 v64, v81, v64
	v_mul_f32_e32 v68, v82, v64
	v_mul_f32_e32 v64, v83, v64
	v_mul_f32_e32 v66, v88, v66
	v_mul_f32_e32 v64, v84, v64
	v_cvt_pk_bf16_f32 v64, v64, v68
	v_cvt_pk_bf16_f32 v65, v67, v65
	v_cvt_pk_bf16_f32 v66, v66, v70
	v_cvt_pk_bf16_f32 v67, v90, v92
	v_cvt_pk_bf16_f32 v68, v91, v80
	v_cvt_pk_bf16_f32 v69, v75, v74
	v_cvt_pk_bf16_f32 v70, v77, v78
	v_cvt_pk_bf16_f32 v71, v76, v79
	v_mul_f32_e32 v177, v72, v73
	s_waitcnt vmcnt(12)
	s_setprio 1
	v_mfma_f32_32x32x16_bf16 v[48:63], v[158:161], v[64:67], v[48:63]
	v_cmp_gt_f32_e64 s[42:43], s1, v177
	s_or_b64 s[92:93], s[92:93], exec
	s_mov_b64 s[44:45], -1
	s_cmp_lg_u64 s[42:43], exec
	v_mfma_f32_32x32x16_bf16 v[32:47], v[150:153], v[64:67], v[32:47]
	s_waitcnt vmcnt(11)
	v_mfma_f32_32x32x16_bf16 v[16:31], v[146:149], v[64:67], v[16:31]
	s_waitcnt vmcnt(9)
	v_mfma_f32_32x32x16_bf16 v[0:15], v[134:137], v[64:67], v[0:15]
	v_mfma_f32_32x32x16_bf16 v[48:63], v[154:157], v[68:71], v[48:63]
	v_mfma_f32_32x32x16_bf16 v[32:47], v[142:145], v[68:71], v[32:47]
	v_mfma_f32_32x32x16_bf16 v[16:31], v[138:141], v[68:71], v[16:31]
	s_waitcnt vmcnt(8)
	v_mfma_f32_32x32x16_bf16 v[0:15], v[130:133], v[68:71], v[0:15]
	s_setprio 0
	s_cbranch_scc1 .LBB0_117
	s_branch .LBB0_118
